# adaLN GEMV loop in prologue: next iteration's 16 strided rows requested into a scratch VGPR before the wait (L2 prefetch, distance 1)
# baseline (speedup 1.0000x reference)
; DI void phase_prep0(const Params& p, char* smem) {
;     ...
; #pragma unroll 16
;       for (int k = kq * 512; k < kq * 512 + 512; ++k) {
;         const float wv = w[(long)k * 6144];
; #pragma unroll
;         for (int r = 0; r < 9; ++r) acc[r] += tl[r * 2048 + k] * wv;
.LBB0_15:
	v_add_co_u32_e64 v20, s[0:1], s7, v8
	v_add_co_u32_e32 v18, vcc, 0xfffa6000, v8
	s_nop 0
	v_addc_co_u32_e64 v21, s[0:1], -1, v9, s[0:1]
	v_add_co_u32_e64 v22, s[0:1], s10, v8
	v_add_u32_e32 v41, s33, v35
	s_nop 0
	v_addc_co_u32_e64 v23, s[0:1], -1, v9, s[0:1]
	v_add_co_u32_e64 v24, s[0:1], s11, v8
	v_addc_co_u32_e32 v19, vcc, -1, v9, vcc
	s_nop 0
	v_addc_co_u32_e64 v25, s[0:1], -1, v9, s[0:1]
	v_add_co_u32_e64 v26, s[0:1], s12, v8
	ds_read_b128 v[42:45], v41
	ds_read_b128 v[46:49], v41 offset:16
	ds_read_b128 v[50:53], v41 offset:32
	ds_read_b128 v[54:57], v41 offset:48
	v_addc_co_u32_e64 v27, s[0:1], -1, v9, s[0:1]
	v_add_co_u32_e64 v28, s[0:1], s13, v8
	global_load_dword v174, v[20:21], off
	global_load_dword v176, v[22:23], off
	global_load_dword v178, v[24:25], off
	global_load_dword v180, v[26:27], off
	v_addc_co_u32_e64 v29, s[0:1], -1, v9, s[0:1]
	v_add_co_u32_e64 v30, s[0:1], s14, v8
	ds_read_b128 v[20:23], v41 offset:8192
	ds_read_b128 v[24:27], v41 offset:8208
	ds_read_b128 v[58:61], v41 offset:16384
	ds_read_b128 v[62:65], v41 offset:16400
	ds_read_b128 v[66:69], v41 offset:24576
	ds_read_b128 v[70:73], v41 offset:24592
	ds_read_b128 v[74:77], v41 offset:32768
	ds_read_b128 v[78:81], v41 offset:32784
	ds_read_b128 v[82:85], v41 offset:40960
	ds_read_b128 v[86:89], v41 offset:40976
	ds_read_b128 v[90:93], v41 offset:49152
	ds_read_b128 v[94:97], v41 offset:49168
	ds_read_b128 v[98:101], v41 offset:57344
	ds_read_b128 v[102:105], v41 offset:57360
	v_addc_co_u32_e64 v31, s[0:1], -1, v9, s[0:1]
	v_add_co_u32_e64 v32, s[0:1], s15, v8
	v_add_u32_e32 v162, 0x10000, v41
	s_nop 0
	v_addc_co_u32_e64 v33, s[0:1], -1, v9, s[0:1]
	v_add_co_u32_e64 v106, s[0:1], s16, v8
	v_add_u32_e32 v163, 0x10010, v41
	s_nop 0
	v_addc_co_u32_e64 v107, s[0:1], -1, v9, s[0:1]
	v_add_co_u32_e64 v108, s[0:1], s17, v8
	global_load_dword v182, v[28:29], off
	global_load_dword v184, v[30:31], off
	global_load_dword v186, v[32:33], off
	s_nop 0
	global_load_dword v32, v[106:107], off
	v_addc_co_u32_e64 v109, s[0:1], -1, v9, s[0:1]
	v_add_co_u32_e64 v110, s[0:1], s18, v8
	v_add_u32_e32 v33, 0x10020, v41
	s_nop 0
	v_addc_co_u32_e64 v111, s[0:1], -1, v9, s[0:1]
	v_add_co_u32_e64 v112, s[0:1], s19, v8
	s_waitcnt lgkmcnt(0)
	v_mov_b32_e32 v204, v58
	v_addc_co_u32_e64 v113, s[0:1], -1, v9, s[0:1]
	v_add_co_u32_e64 v114, s[0:1], s21, v8
	v_mov_b32_e32 v205, v20
	s_nop 0
	v_addc_co_u32_e64 v115, s[0:1], -1, v9, s[0:1]
	v_add_co_u32_e64 v158, s[0:1], s22, v8
	global_load_dword v188, v[108:109], off
	global_load_dword v190, v[110:111], off
	global_load_dword v192, v[112:113], off
	global_load_dword v194, v[114:115], off
	v_addc_co_u32_e64 v159, s[0:1], -1, v9, s[0:1]
	v_add_co_u32_e64 v160, s[0:1], s23, v8
	ds_read_b128 v[28:31], v41 offset:8224
	ds_read_b128 v[106:109], v41 offset:8240
	ds_read_b128 v[110:113], v41 offset:16416
	ds_read_b128 v[114:117], v41 offset:16432
	ds_read_b128 v[118:121], v41 offset:24608
	ds_read_b128 v[122:125], v41 offset:24624
	ds_read_b128 v[126:129], v41 offset:32800
	ds_read_b128 v[130:133], v41 offset:32816
	ds_read_b128 v[134:137], v41 offset:40992
	ds_read_b128 v[138:141], v41 offset:41008
	ds_read_b128 v[142:145], v41 offset:49184
	ds_read_b128 v[146:149], v41 offset:49200
	ds_read_b128 v[150:153], v41 offset:57376
	ds_read_b128 v[154:157], v41 offset:57392
	v_addc_co_u32_e64 v161, s[0:1], -1, v9, s[0:1]
	global_load_dword v196, v[158:159], off
	global_load_dword v198, v[160:161], off
	global_load_dword v200, v[8:9], off
	v_add_u32_e32 v41, 0x10030, v41
	global_load_dword v18, v[18:19], off
	ds_read_b128 v[158:161], v162
	ds_read_b128 v[162:165], v163
	ds_read_b128 v[166:169], v33
	ds_read_b128 v[170:173], v41
	v_mov_b32_e32 v206, v74
	v_mov_b32_e32 v207, v66
	v_mov_b32_e32 v208, v90
	v_mov_b32_e32 v209, v82
	v_mov_b32_e32 v211, v98
	s_waitcnt lgkmcnt(0)
	v_mov_b32_e32 v210, v158
	v_mov_b32_e32 v20, v59
	v_mov_b32_e32 v66, v75
	v_mov_b32_e32 v82, v91
	v_mov_b32_e32 v98, v159
	v_mov_b32_e32 v58, v60
	v_mov_b32_e32 v59, v22
	v_mov_b32_e32 v74, v76
	v_mov_b32_e32 v75, v68
	v_mov_b32_e32 v90, v92
	v_mov_b32_e32 v91, v84
	v_mov_b32_e32 v213, v100
	v_mov_b32_e32 v212, v160
	v_mov_b32_e32 v22, v61
	v_mov_b32_e32 v68, v77
	v_mov_b32_e32 v84, v93
	v_mov_b32_e32 v100, v161
	v_mov_b32_e32 v60, v62
	v_mov_b32_e32 v61, v24
	v_mov_b32_e32 v76, v78
	v_mov_b32_e32 v77, v70
	v_mov_b32_e32 v92, v94
	v_mov_b32_e32 v93, v86
	v_mov_b32_e32 v215, v102
	v_mov_b32_e32 v214, v162
	v_mov_b32_e32 v24, v63
	v_mov_b32_e32 v70, v79
	v_mov_b32_e32 v86, v95
	v_mov_b32_e32 v102, v163
	v_mov_b32_e32 v62, v64
	v_mov_b32_e32 v63, v26
	v_mov_b32_e32 v78, v80
	v_mov_b32_e32 v79, v72
	v_mov_b32_e32 v94, v96
	v_mov_b32_e32 v95, v88
	v_mov_b32_e32 v217, v104
	v_mov_b32_e32 v216, v164
	v_mov_b32_e32 v26, v65
	v_mov_b32_e32 v72, v81
	v_mov_b32_e32 v88, v97
	v_mov_b32_e32 v104, v165
	v_mov_b32_e32 v64, v110
	v_mov_b32_e32 v65, v28
	v_mov_b32_e32 v80, v126
	v_mov_b32_e32 v81, v118
	v_mov_b32_e32 v96, v142
	v_mov_b32_e32 v97, v134
	v_mov_b32_e32 v219, v150
	v_mov_b32_e32 v218, v166
	v_mov_b32_e32 v28, v111
	v_mov_b32_e32 v118, v127
	v_mov_b32_e32 v134, v143
	v_mov_b32_e32 v150, v167
	v_mov_b32_e32 v110, v112
	v_mov_b32_e32 v111, v30
	v_mov_b32_e32 v126, v128
	v_mov_b32_e32 v127, v120
	v_mov_b32_e32 v142, v144
	v_mov_b32_e32 v143, v136
	v_mov_b32_e32 v221, v152
	v_mov_b32_e32 v220, v168
	v_mov_b32_e32 v30, v113
	v_mov_b32_e32 v120, v129
	v_mov_b32_e32 v136, v145
	v_mov_b32_e32 v152, v169
	v_mov_b32_e32 v112, v114
	v_mov_b32_e32 v113, v106
	v_mov_b32_e32 v128, v130
	v_mov_b32_e32 v129, v122
	v_mov_b32_e32 v144, v146
	v_mov_b32_e32 v145, v138
	v_mov_b32_e32 v223, v154
	v_mov_b32_e32 v222, v170
	s_cmpk_eq_i32 s33, 0x7c0
	s_cbranch_scc1 .Lgv_last
; DI void phase_prep0(const Params& p, char* smem) {
;     ...
; #pragma unroll 16
;       for (int k = kq * 512; k < kq * 512 + 512; ++k) {
;         const float wv = w[(long)k * 6144];
; #pragma unroll
	s_mov_b32 s98, 0x6000
	s_mov_b32 s99, 0
	v_lshl_add_u64 v[252:253], s[98:99], 0, v[8:9]
	global_load_dword v226, v[252:253], off
	v_lshl_add_u64 v[252:253], s[98:99], 0, v[252:253]
	global_load_dword v226, v[252:253], off
	v_lshl_add_u64 v[252:253], s[98:99], 0, v[252:253]
	global_load_dword v226, v[252:253], off
	v_lshl_add_u64 v[252:253], s[98:99], 0, v[252:253]
	global_load_dword v226, v[252:253], off
	v_lshl_add_u64 v[252:253], s[98:99], 0, v[252:253]
	global_load_dword v226, v[252:253], off
	v_lshl_add_u64 v[252:253], s[98:99], 0, v[252:253]
	global_load_dword v226, v[252:253], off
	v_lshl_add_u64 v[252:253], s[98:99], 0, v[252:253]
	global_load_dword v226, v[252:253], off
	v_lshl_add_u64 v[252:253], s[98:99], 0, v[252:253]
	global_load_dword v226, v[252:253], off
	v_lshl_add_u64 v[252:253], s[98:99], 0, v[252:253]
	global_load_dword v226, v[252:253], off
	v_lshl_add_u64 v[252:253], s[98:99], 0, v[252:253]
	global_load_dword v226, v[252:253], off
	v_lshl_add_u64 v[252:253], s[98:99], 0, v[252:253]
	global_load_dword v226, v[252:253], off
	v_lshl_add_u64 v[252:253], s[98:99], 0, v[252:253]
	global_load_dword v226, v[252:253], off
	v_lshl_add_u64 v[252:253], s[98:99], 0, v[252:253]
	global_load_dword v226, v[252:253], off
	v_lshl_add_u64 v[252:253], s[98:99], 0, v[252:253]
	global_load_dword v226, v[252:253], off
	v_lshl_add_u64 v[252:253], s[98:99], 0, v[252:253]
	global_load_dword v226, v[252:253], off
	v_lshl_add_u64 v[252:253], s[98:99], 0, v[252:253]
	global_load_dword v226, v[252:253], off
	s_waitcnt vmcnt(16)
	s_branch .Lgv_join

; DI void phase_prep0(const Params& p, char* smem) {
;     ...
; #pragma unroll 16
;       for (int k = kq * 512; k < kq * 512 + 512; ++k) {
;         const float wv = w[(long)k * 6144];
; #pragma unroll
;         for (int r = 0; r < 9; ++r) acc[r] += tl[r * 2048 + k] * wv;
.Lgv_join:
	v_fmac_f32_e32 v40, v18, v42
	v_pk_fma_f32 v[16:17], v[18:19], v[204:205], v[16:17] op_sel_hi:[0,1,1]
	v_pk_fma_f32 v[14:15], v[18:19], v[206:207], v[14:15] op_sel_hi:[0,1,1]
	v_pk_fma_f32 v[12:13], v[18:19], v[208:209], v[12:13] op_sel_hi:[0,1,1]
	v_pk_fma_f32 v[10:11], v[18:19], v[210:211], v[10:11] op_sel_hi:[0,1,1]
	v_fmac_f32_e32 v40, v174, v43
	v_pk_fma_f32 v[16:17], v[174:175], v[20:21], v[16:17] op_sel_hi:[0,1,1]
	v_pk_fma_f32 v[14:15], v[174:175], v[66:67], v[14:15] op_sel_hi:[0,1,1]
	v_pk_fma_f32 v[12:13], v[174:175], v[82:83], v[12:13] op_sel_hi:[0,1,1]
	v_pk_fma_f32 v[10:11], v[174:175], v[98:99], v[10:11] op_sel_hi:[0,1,1]
	v_fmac_f32_e32 v40, v176, v44
	v_pk_fma_f32 v[16:17], v[176:177], v[58:59], v[16:17] op_sel_hi:[0,1,1]
	v_pk_fma_f32 v[14:15], v[176:177], v[74:75], v[14:15] op_sel_hi:[0,1,1]
	v_pk_fma_f32 v[12:13], v[176:177], v[90:91], v[12:13] op_sel_hi:[0,1,1]
	v_pk_fma_f32 v[10:11], v[176:177], v[212:213], v[10:11] op_sel_hi:[0,1,1]
	v_fmac_f32_e32 v40, v178, v45
	v_pk_fma_f32 v[16:17], v[178:179], v[22:23], v[16:17] op_sel_hi:[0,1,1]
	v_pk_fma_f32 v[14:15], v[178:179], v[68:69], v[14:15] op_sel_hi:[0,1,1]
	v_pk_fma_f32 v[12:13], v[178:179], v[84:85], v[12:13] op_sel_hi:[0,1,1]
	v_pk_fma_f32 v[10:11], v[178:179], v[100:101], v[10:11] op_sel_hi:[0,1,1]
	v_fmac_f32_e32 v40, v180, v46
	v_pk_fma_f32 v[16:17], v[180:181], v[60:61], v[16:17] op_sel_hi:[0,1,1]
	v_pk_fma_f32 v[14:15], v[180:181], v[76:77], v[14:15] op_sel_hi:[0,1,1]
	v_pk_fma_f32 v[12:13], v[180:181], v[92:93], v[12:13] op_sel_hi:[0,1,1]
	v_pk_fma_f32 v[10:11], v[180:181], v[214:215], v[10:11] op_sel_hi:[0,1,1]
	v_fmac_f32_e32 v40, v182, v47
	v_pk_fma_f32 v[16:17], v[182:183], v[24:25], v[16:17] op_sel_hi:[0,1,1]
	v_pk_fma_f32 v[14:15], v[182:183], v[70:71], v[14:15] op_sel_hi:[0,1,1]
	v_pk_fma_f32 v[12:13], v[182:183], v[86:87], v[12:13] op_sel_hi:[0,1,1]
	v_pk_fma_f32 v[10:11], v[182:183], v[102:103], v[10:11] op_sel_hi:[0,1,1]
	v_fmac_f32_e32 v40, v184, v48
	v_pk_fma_f32 v[16:17], v[184:185], v[62:63], v[16:17] op_sel_hi:[0,1,1]
	v_pk_fma_f32 v[14:15], v[184:185], v[78:79], v[14:15] op_sel_hi:[0,1,1]
	v_pk_fma_f32 v[12:13], v[184:185], v[94:95], v[12:13] op_sel_hi:[0,1,1]
	v_pk_fma_f32 v[10:11], v[184:185], v[216:217], v[10:11] op_sel_hi:[0,1,1]
	v_fmac_f32_e32 v40, v186, v49
	v_pk_fma_f32 v[16:17], v[186:187], v[26:27], v[16:17] op_sel_hi:[0,1,1]
	v_pk_fma_f32 v[14:15], v[186:187], v[72:73], v[14:15] op_sel_hi:[0,1,1]
	v_pk_fma_f32 v[12:13], v[186:187], v[88:89], v[12:13] op_sel_hi:[0,1,1]
	v_pk_fma_f32 v[10:11], v[186:187], v[104:105], v[10:11] op_sel_hi:[0,1,1]
	v_fmac_f32_e32 v40, v32, v50
	v_pk_fma_f32 v[16:17], v[32:33], v[64:65], v[16:17] op_sel_hi:[0,1,1]
	v_pk_fma_f32 v[14:15], v[32:33], v[80:81], v[14:15] op_sel_hi:[0,1,1]
	v_pk_fma_f32 v[12:13], v[32:33], v[96:97], v[12:13] op_sel_hi:[0,1,1]
	v_pk_fma_f32 v[10:11], v[32:33], v[218:219], v[10:11] op_sel_hi:[0,1,1]
	v_fmac_f32_e32 v40, v188, v51
	v_pk_fma_f32 v[16:17], v[188:189], v[28:29], v[16:17] op_sel_hi:[0,1,1]
	v_pk_fma_f32 v[14:15], v[188:189], v[118:119], v[14:15] op_sel_hi:[0,1,1]
	v_pk_fma_f32 v[12:13], v[188:189], v[134:135], v[12:13] op_sel_hi:[0,1,1]
	v_pk_fma_f32 v[10:11], v[188:189], v[150:151], v[10:11] op_sel_hi:[0,1,1]
	v_fmac_f32_e32 v40, v190, v52
	v_pk_fma_f32 v[16:17], v[190:191], v[110:111], v[16:17] op_sel_hi:[0,1,1]
	v_pk_fma_f32 v[14:15], v[190:191], v[126:127], v[14:15] op_sel_hi:[0,1,1]
	v_pk_fma_f32 v[12:13], v[190:191], v[142:143], v[12:13] op_sel_hi:[0,1,1]
	v_pk_fma_f32 v[10:11], v[190:191], v[220:221], v[10:11] op_sel_hi:[0,1,1]
	v_fmac_f32_e32 v40, v192, v53
	v_pk_fma_f32 v[16:17], v[192:193], v[30:31], v[16:17] op_sel_hi:[0,1,1]
	v_pk_fma_f32 v[14:15], v[192:193], v[120:121], v[14:15] op_sel_hi:[0,1,1]
	v_pk_fma_f32 v[12:13], v[192:193], v[136:137], v[12:13] op_sel_hi:[0,1,1]
	v_pk_fma_f32 v[10:11], v[192:193], v[152:153], v[10:11] op_sel_hi:[0,1,1]
	v_mov_b32_e32 v106, v115
	v_mov_b32_e32 v122, v131
	v_mov_b32_e32 v138, v147
	v_mov_b32_e32 v154, v171
	v_fmac_f32_e32 v40, v194, v54
	v_pk_fma_f32 v[16:17], v[194:195], v[112:113], v[16:17] op_sel_hi:[0,1,1]
	v_pk_fma_f32 v[14:15], v[194:195], v[128:129], v[14:15] op_sel_hi:[0,1,1]
	v_pk_fma_f32 v[12:13], v[194:195], v[144:145], v[12:13] op_sel_hi:[0,1,1]
	v_pk_fma_f32 v[10:11], v[194:195], v[222:223], v[10:11] op_sel_hi:[0,1,1]
	v_mov_b32_e32 v114, v116
	v_mov_b32_e32 v115, v108
	v_mov_b32_e32 v130, v132
	v_mov_b32_e32 v131, v124
	v_mov_b32_e32 v146, v148
	v_mov_b32_e32 v147, v140
	v_mov_b32_e32 v225, v156
	v_mov_b32_e32 v224, v172
	v_fmac_f32_e32 v40, v196, v55
	v_pk_fma_f32 v[16:17], v[196:197], v[106:107], v[16:17] op_sel_hi:[0,1,1]
	v_pk_fma_f32 v[14:15], v[196:197], v[122:123], v[14:15] op_sel_hi:[0,1,1]
	v_pk_fma_f32 v[12:13], v[196:197], v[138:139], v[12:13] op_sel_hi:[0,1,1]
	v_pk_fma_f32 v[10:11], v[196:197], v[154:155], v[10:11] op_sel_hi:[0,1,1]
	s_add_i32 s33, s33, 64
	v_mov_b32_e32 v108, v117
	v_mov_b32_e32 v124, v133
	v_mov_b32_e32 v140, v149
	v_mov_b32_e32 v156, v173
	v_fmac_f32_e32 v40, v198, v56
	v_pk_fma_f32 v[16:17], v[198:199], v[114:115], v[16:17] op_sel_hi:[0,1,1]
	v_pk_fma_f32 v[14:15], v[198:199], v[130:131], v[14:15] op_sel_hi:[0,1,1]
	v_pk_fma_f32 v[12:13], v[198:199], v[146:147], v[12:13] op_sel_hi:[0,1,1]
	v_pk_fma_f32 v[10:11], v[198:199], v[224:225], v[10:11] op_sel_hi:[0,1,1]
	v_lshl_add_u64 v[8:9], v[8:9], 0, s[4:5]
	s_cmpk_eq_i32 s33, 0x800
	v_fmac_f32_e32 v40, v200, v57
	v_pk_fma_f32 v[16:17], v[200:201], v[108:109], v[16:17] op_sel_hi:[0,1,1]
	v_pk_fma_f32 v[14:15], v[200:201], v[124:125], v[14:15] op_sel_hi:[0,1,1]
	v_pk_fma_f32 v[12:13], v[200:201], v[140:141], v[12:13] op_sel_hi:[0,1,1]
	v_pk_fma_f32 v[10:11], v[200:201], v[156:157], v[10:11] op_sel_hi:[0,1,1]
	s_cbranch_scc0 .LBB0_15
;   DI const float* ada_b() const { return (const float*)sp[5]; }
; DI void phase_prep0(const Params& p, char* smem) {
;     ...
;       __syncthreads();
;       float* red = tl;
;       for (int r = 0; r < 9; ++r) red[(kq * 9 + r) * 64 + (tid & 63)] = acc[r];
;       __syncthreads();
;       if (tid < 64) {
;         for (int r = 0; r < 9; ++r) {
;           float sm = red[r * 64 + tid] + red[(9 + r) * 64 + tid] + red[(18 + r) * 64 + tid] + red[(27 + r) * 64 + tid];
;           P_MOD[((long)layer * 9 + r) * 6144 + col] = sm + p.ada_b()[layer * 6144 + col];
;         }
	s_barrier
	ds_write2st64_b32 v34, v40, v17 offset1:1
	ds_write2st64_b32 v34, v16, v15 offset0:2 offset1:3
	ds_write2st64_b32 v34, v14, v13 offset0:4 offset1:5
	ds_write2st64_b32 v34, v12, v11 offset0:6 offset1:7
	ds_write_b32 v34, v10 offset:2048
	s_waitcnt lgkmcnt(0)
	s_barrier
	s_and_saveexec_b64 s[0:1], s[2:3]
	s_cbranch_execz .LBB0_13
	ds_read_b64 v[8:9], v38
	s_mul_i32 s33, s31, 0x1800
	v_add_u32_e32 v10, s33, v6
	v_ashrrev_i32_e32 v11, 31, v10
	v_lshl_add_u64 v[6:7], v[6:7], 2, s[48:49]
	s_waitcnt lgkmcnt(0)
	v_lshl_add_u64 v[8:9], v[10:11], 2, v[8:9]
	global_load_dword v48, v[8:9], off
	ds_read2st64_b32 v[10:11], v1 offset0:8 offset1:9
	ds_read2st64_b32 v[12:13], v1 offset0:10 offset1:11
	ds_read2st64_b32 v[14:15], v1 offset0:12 offset1:13
	ds_read2st64_b32 v[16:17], v1 offset0:14 offset1:15
	ds_read2st64_b32 v[18:19], v1 offset1:1
	ds_read2st64_b32 v[20:21], v1 offset0:2 offset1:3
	ds_read2st64_b32 v[22:23], v1 offset0:4 offset1:5
	ds_read2st64_b32 v[24:25], v1 offset0:6 offset1:7
	ds_read2st64_b32 v[26:27], v1 offset0:26 offset1:27
	ds_read2st64_b32 v[28:29], v1 offset0:28 offset1:29
	ds_read2st64_b32 v[30:31], v1 offset0:30 offset1:31
	ds_read2st64_b32 v[32:33], v1 offset0:24 offset1:25
	ds_read2st64_b32 v[40:41], v1 offset0:18 offset1:19
	ds_read2st64_b32 v[42:43], v1 offset0:20 offset1:21
	ds_read2st64_b32 v[44:45], v1 offset0:22 offset1:23
	ds_read2st64_b32 v[46:47], v1 offset0:16 offset1:17
	s_waitcnt lgkmcnt(0)
	v_add_f32_e32 v11, v18, v11
	v_add_f32_e32 v11, v11, v40
	v_add_f32_e32 v11, v11, v27
	v_mad_i64_i32 v[6:7], s[34:35], s31, v39, v[6:7]
	v_add_f32_e32 v12, v19, v12
	v_add_f32_e32 v12, v12, v41
	v_add_f32_e32 v12, v12, v28
	v_add_f32_e32 v14, v21, v14
	v_add_f32_e32 v14, v14, v43
	v_add_f32_e32 v14, v14, v30
	v_add_f32_e32 v16, v23, v16
	v_add_f32_e32 v16, v16, v45
	s_waitcnt vmcnt(0)
	v_add_f32_e32 v11, v11, v48
	global_store_dword v[6:7], v11, off
	global_load_dword v11, v[8:9], off
	v_add_co_u32_e32 v48, vcc, s6, v6
	s_waitcnt vmcnt(0) lgkmcnt(0)
	v_add_f32_e32 v11, v12, v11
	v_addc_co_u32_e32 v49, vcc, 0, v7, vcc
	global_store_dword v[48:49], v11, off
	global_load_dword v11, v[8:9], off
	v_add_f32_e32 v12, v20, v13
	v_add_f32_e32 v12, v12, v42
	v_add_co_u32_e32 v18, vcc, s24, v6
	v_add_f32_e32 v12, v12, v29
	s_nop 0
	v_addc_co_u32_e32 v19, vcc, 0, v7, vcc
	s_waitcnt vmcnt(0) lgkmcnt(0)
	v_add_f32_e32 v11, v12, v11
	global_store_dword v[18:19], v11, off
	global_load_dword v11, v[8:9], off
	v_add_co_u32_e32 v12, vcc, s25, v6
	s_waitcnt vmcnt(0) lgkmcnt(0)
	v_add_f32_e32 v11, v14, v11
	v_addc_co_u32_e32 v13, vcc, 0, v7, vcc
	global_store_dword v[12:13], v11, off
	global_load_dword v11, v[8:9], off
	v_add_f32_e32 v14, v22, v15
	v_add_f32_e32 v14, v14, v44
	v_add_co_u32_e32 v12, vcc, s26, v6
	v_add_f32_e32 v14, v14, v31
	s_nop 0
	v_addc_co_u32_e32 v13, vcc, 0, v7, vcc
	v_add_co_u32_e32 v18, vcc, s27, v6
	s_waitcnt vmcnt(0) lgkmcnt(0)
	v_add_f32_e32 v11, v14, v11
	global_store_dword v[12:13], v11, off
	global_load_dword v11, v[8:9], off
	ds_read2st64_b32 v[12:13], v1 offset0:32 offset1:33
	ds_read2st64_b32 v[14:15], v1 offset0:34 offset1:35
	v_addc_co_u32_e32 v19, vcc, 0, v7, vcc
	s_waitcnt lgkmcnt(0)
	v_add_f32_e32 v12, v16, v12
	v_add_f32_e32 v16, v25, v46
	v_add_f32_e32 v16, v16, v33
	v_add_f32_e32 v14, v16, v14
	s_waitcnt vmcnt(0)
	v_add_f32_e32 v11, v12, v11
	global_store_dword v[18:19], v11, off
	global_load_dword v11, v[8:9], off
	v_add_f32_e32 v12, v24, v17
	v_add_f32_e32 v12, v12, v32
	v_add_co_u32_e32 v18, vcc, s28, v6
	v_add_f32_e32 v12, v12, v13
	s_nop 0
	v_addc_co_u32_e32 v19, vcc, 0, v7, vcc
	s_waitcnt vmcnt(0) lgkmcnt(0)
	v_add_f32_e32 v11, v12, v11
	global_store_dword v[18:19], v11, off
	global_load_dword v11, v[8:9], off
	v_add_co_u32_e32 v12, vcc, s29, v6
	s_waitcnt vmcnt(0) lgkmcnt(0)
	v_add_f32_e32 v11, v14, v11
	v_addc_co_u32_e32 v13, vcc, 0, v7, vcc
	global_store_dword v[12:13], v11, off
	global_load_dword v8, v[8:9], off
	v_add_f32_e32 v9, v10, v47
	v_add_f32_e32 v9, v9, v26
	v_add_co_u32_e32 v6, vcc, 0x30000, v6
	v_add_f32_e32 v9, v9, v15
	s_nop 0
	v_addc_co_u32_e32 v7, vcc, 0, v7, vcc
	s_waitcnt vmcnt(0) lgkmcnt(0)
	v_add_f32_e32 v8, v9, v8
	global_store_dword v[6:7], v8, off
	s_branch .LBB0_13

; __global__ void __launch_bounds__(NT, 2) mega(KArgs ka) {
	.amdhsa_kernel _Z4mega5KArgs
		.amdhsa_group_segment_fixed_size 74456
		.amdhsa_private_segment_fixed_size 0
		.amdhsa_kernarg_size 448
		.amdhsa_user_sgpr_count 2
		.amdhsa_user_sgpr_dispatch_ptr 0
		.amdhsa_user_sgpr_queue_ptr 0
		.amdhsa_user_sgpr_kernarg_segment_ptr 1
		.amdhsa_user_sgpr_dispatch_id 0
		.amdhsa_user_sgpr_kernarg_preload_length 0
		.amdhsa_user_sgpr_kernarg_preload_offset 0
		.amdhsa_user_sgpr_private_segment_size 0
		.amdhsa_uses_dynamic_stack 0
		.amdhsa_enable_private_segment 0
		.amdhsa_system_sgpr_workgroup_id_x 1
		.amdhsa_system_sgpr_workgroup_id_y 0
		.amdhsa_system_sgpr_workgroup_id_z 0
		.amdhsa_system_sgpr_workgroup_info 0
		.amdhsa_system_vgpr_workitem_id 2
		.amdhsa_next_free_vgpr 256
		.amdhsa_next_free_sgpr 102
		.amdhsa_accum_offset 256
		.amdhsa_reserve_vcc 1
		.amdhsa_float_round_mode_32 0
		.amdhsa_float_round_mode_16_64 0
		.amdhsa_float_denorm_mode_32 3
		.amdhsa_float_denorm_mode_16_64 3
		.amdhsa_dx10_clamp 1
		.amdhsa_ieee_mode 1
		.amdhsa_fp16_overflow 0
		.amdhsa_tg_split 0
		.amdhsa_exception_fp_ieee_invalid_op 0
		.amdhsa_exception_fp_denorm_src 0
		.amdhsa_exception_fp_ieee_div_zero 0
		.amdhsa_exception_fp_ieee_overflow 0
		.amdhsa_exception_fp_ieee_underflow 0
		.amdhsa_exception_fp_ieee_inexact 0
		.amdhsa_exception_int_div_zero 0
	.end_amdhsa_kernel

; __global__ void __launch_bounds__(NT, 2) mega(KArgs ka) {
amdhsa.kernels:
  - .agpr_count:     0
    .args:
      - .offset:         0
        .size:           192
        .value_kind:     by_value
      - .offset:         192
        .size:           4
        .value_kind:     hidden_block_count_x
      - .offset:         196
        .size:           4
        .value_kind:     hidden_block_count_y
      - .offset:         200
        .size:           4
        .value_kind:     hidden_block_count_z
      - .offset:         204
        .size:           2
        .value_kind:     hidden_group_size_x
      - .offset:         206
        .size:           2
        .value_kind:     hidden_group_size_y
      - .offset:         208
        .size:           2
        .value_kind:     hidden_group_size_z
      - .offset:         210
        .size:           2
        .value_kind:     hidden_remainder_x
      - .offset:         212
        .size:           2
        .value_kind:     hidden_remainder_y
      - .offset:         214
        .size:           2
        .value_kind:     hidden_remainder_z
      - .offset:         232
        .size:           8
        .value_kind:     hidden_global_offset_x
      - .offset:         240
        .size:           8
        .value_kind:     hidden_global_offset_y
      - .offset:         248
        .size:           8
        .value_kind:     hidden_global_offset_z
      - .offset:         256
        .size:           2
        .value_kind:     hidden_grid_dims
      - .offset:         280
        .size:           8
        .value_kind:     hidden_multigrid_sync_arg
    .group_segment_fixed_size: 74456
    .kernarg_segment_align: 8
    .kernarg_segment_size: 448
    .language:       OpenCL C
    .language_version:
      - 2
      - 0
    .max_flat_workgroup_size: 256
    .name:           _Z4mega5KArgs
    .private_segment_fixed_size: 0
    .sgpr_count:     108
    .sgpr_spill_count: 120
    .symbol:         _Z4mega5KArgs.kd
    .uniform_work_group_size: 1
    .uses_dynamic_stack: false
    .vgpr_count:     256
    .vgpr_spill_count: 0
    .wavefront_size: 64
